# grid barrier poll: the 16 arrival-counter loads issued back to back and summed after one wait (9 in-loop barrier instances), instead of 16 serialised load-wait-add round trips
# speedup vs baseline: 1.0076x; 1.0002x over previous
; __device__ __forceinline__ unsigned xb_ld(unsigned* p)              { return __hip_atomic_load(p, __ATOMIC_RELAXED, __HIP_MEMORY_SCOPE_AGENT); }
; __device__ __forceinline__ void xcd_barrier_complete(unsigned* bar, unsigned x, unsigned& nloc, unsigned& nx) {
;     const unsigned G = gridDim.x * gridDim.y * gridDim.z;
;     unsigned sum, cnt, mine, sp = 0u;
;     for (;;) {
;         sum = 0u; cnt = 0u; mine = 0u;
; #pragma unroll
;         for (unsigned j = 0; j < 16; ++j) { const unsigned c = xb_ld(&bar[XB_XCNT(j)]); sum += c; cnt += (c > 0u) ? 1u : 0u; mine = (j == x) ? c : mine; }
;         if (sum == G) break;
;         __builtin_amdgcn_s_sleep(1);
;         if ((++sp & 255u) == 0u) { if (xb_ld(&bar[XB_TMO])) break; if (sp > XB_SPIN_CAP) { atomicAdd(&bar[XB_TMO], 1u); break; } }
;     }
;     nloc = mine > 0u ? mine : 1u; nx = cnt > 0u ? cnt : 1u;
; }
.LBB0_202:
	v_readlane_b32 s4, v249, 41
	v_readlane_b32 s5, v249, 42
	v_readlane_b32 s19, v253, 41
	s_mov_b64 s[26:27], -1
	s_waitcnt lgkmcnt(0)
	s_nop 1
	global_load_dword v0, v1, s[4:5] sc1
	v_readlane_b32 s4, v249, 43
	v_readlane_b32 s5, v249, 44
	s_nop 4
	global_load_dword v2, v1, s[4:5] sc1
	v_readlane_b32 s4, v249, 45
	v_readlane_b32 s5, v249, 46
	s_nop 4
	global_load_dword v3, v1, s[4:5] sc1
	v_readlane_b32 s4, v249, 47
	v_readlane_b32 s5, v249, 48
	s_nop 4
	global_load_dword v4, v1, s[4:5] sc1
	v_readlane_b32 s4, v249, 49
	v_readlane_b32 s5, v249, 50
	s_nop 4
	global_load_dword v5, v1, s[4:5] sc1
	v_readlane_b32 s4, v249, 51
	v_readlane_b32 s5, v249, 52
	s_nop 4
	global_load_dword v6, v1, s[4:5] sc1
	v_readlane_b32 s4, v249, 53
	v_readlane_b32 s5, v249, 54
	s_nop 4
	global_load_dword v7, v1, s[4:5] sc1
	v_readlane_b32 s4, v249, 55
	v_readlane_b32 s5, v249, 56
	s_nop 4
	global_load_dword v8, v1, s[4:5] sc1
	v_readlane_b32 s4, v249, 57
	v_readlane_b32 s5, v249, 58
	s_nop 4
	global_load_dword v9, v1, s[4:5] sc1
	v_readlane_b32 s4, v249, 59
	v_readlane_b32 s5, v249, 60
	s_nop 4
	global_load_dword v10, v1, s[4:5] sc1
	v_readlane_b32 s4, v249, 61
	v_readlane_b32 s5, v249, 62
	s_nop 4
	global_load_dword v11, v1, s[4:5] sc1
	v_readlane_b32 s4, v249, 63
	v_readlane_b32 s5, v250, 0
	s_nop 4
	global_load_dword v12, v1, s[4:5] sc1
	v_readlane_b32 s4, v250, 1
	v_readlane_b32 s5, v250, 2
	s_nop 4
	global_load_dword v13, v1, s[4:5] sc1
	v_readlane_b32 s4, v250, 3
	v_readlane_b32 s5, v250, 4
	s_nop 4
	global_load_dword v14, v1, s[4:5] sc1
	v_readlane_b32 s4, v250, 5
	v_readlane_b32 s5, v250, 6
	s_nop 4
	global_load_dword v15, v1, s[4:5] sc1
	v_readlane_b32 s4, v250, 7
	v_readlane_b32 s5, v250, 8
	s_nop 4
	global_load_dword v16, v1, s[4:5] sc1
	s_mov_b64 s[4:5], -1
	s_waitcnt vmcnt(0)
	v_add_u32_e32 v17, v2, v0
	v_add_u32_e32 v17, v17, v3
	v_add_u32_e32 v17, v17, v4
	v_add_u32_e32 v17, v17, v5
	v_add_u32_e32 v17, v17, v6
	v_add_u32_e32 v17, v17, v7
	v_add_u32_e32 v17, v17, v8
	v_add_u32_e32 v17, v17, v9
	v_add_u32_e32 v17, v17, v10
	v_add_u32_e32 v17, v17, v11
	v_add_u32_e32 v17, v17, v12
	v_add_u32_e32 v17, v17, v13
	v_add_u32_e32 v17, v17, v14
	v_add_u32_e32 v17, v17, v15
	v_add_u32_e32 v17, v17, v16
	v_cmp_eq_u32_e32 vcc, s19, v17
	s_cbranch_vccnz .LBB0_201
	s_and_b32 s4, s18, 0xff
	s_cmp_eq_u32 s4, 0
	s_mov_b64 s[4:5], -1
	s_mov_b64 s[40:41], -1
	s_sleep 1
	s_cbranch_scc1 .LBB0_206
	s_and_b64 vcc, exec, s[40:41]
	s_cbranch_vccz .LBB0_201

; __device__ __forceinline__ unsigned xb_ld(unsigned* p)              { return __hip_atomic_load(p, __ATOMIC_RELAXED, __HIP_MEMORY_SCOPE_AGENT); }
; __device__ __forceinline__ void xcd_barrier_complete(unsigned* bar, unsigned x, unsigned& nloc, unsigned& nx) {
;     const unsigned G = gridDim.x * gridDim.y * gridDim.z;
;     unsigned sum, cnt, mine, sp = 0u;
;     for (;;) {
;         sum = 0u; cnt = 0u; mine = 0u;
; #pragma unroll
;         for (unsigned j = 0; j < 16; ++j) { const unsigned c = xb_ld(&bar[XB_XCNT(j)]); sum += c; cnt += (c > 0u) ? 1u : 0u; mine = (j == x) ? c : mine; }
;         if (sum == G) break;
;         __builtin_amdgcn_s_sleep(1);
;         if ((++sp & 255u) == 0u) { if (xb_ld(&bar[XB_TMO])) break; if (sp > XB_SPIN_CAP) { atomicAdd(&bar[XB_TMO], 1u); break; } }
;     }
;     nloc = mine > 0u ? mine : 1u; nx = cnt > 0u ? cnt : 1u;
; }
.LBB0_328:
	v_readlane_b32 s4, v249, 41
	v_readlane_b32 s5, v249, 42
	v_readlane_b32 s19, v253, 41
	s_mov_b64 s[26:27], -1
	s_nop 2
	global_load_dword v0, v1, s[4:5] sc1
	v_readlane_b32 s4, v249, 43
	v_readlane_b32 s5, v249, 44
	s_waitcnt lgkmcnt(0)
	s_nop 4
	global_load_dword v2, v1, s[4:5] sc1
	v_readlane_b32 s4, v249, 45
	v_readlane_b32 s5, v249, 46
	s_nop 4
	global_load_dword v3, v1, s[4:5] sc1
	v_readlane_b32 s4, v249, 47
	v_readlane_b32 s5, v249, 48
	s_nop 4
	global_load_dword v4, v1, s[4:5] sc1
	v_readlane_b32 s4, v249, 49
	v_readlane_b32 s5, v249, 50
	s_nop 4
	global_load_dword v5, v1, s[4:5] sc1
	v_readlane_b32 s4, v249, 51
	v_readlane_b32 s5, v249, 52
	s_nop 4
	global_load_dword v6, v1, s[4:5] sc1
	v_readlane_b32 s4, v249, 53
	v_readlane_b32 s5, v249, 54
	s_nop 4
	global_load_dword v7, v1, s[4:5] sc1
	v_readlane_b32 s4, v249, 55
	v_readlane_b32 s5, v249, 56
	s_nop 4
	global_load_dword v8, v1, s[4:5] sc1
	v_readlane_b32 s4, v249, 57
	v_readlane_b32 s5, v249, 58
	s_nop 4
	global_load_dword v9, v1, s[4:5] sc1
	v_readlane_b32 s4, v249, 59
	v_readlane_b32 s5, v249, 60
	s_nop 4
	global_load_dword v10, v1, s[4:5] sc1
	v_readlane_b32 s4, v249, 61
	v_readlane_b32 s5, v249, 62
	s_nop 4
	global_load_dword v11, v1, s[4:5] sc1
	v_readlane_b32 s4, v249, 63
	v_readlane_b32 s5, v250, 0
	s_nop 4
	global_load_dword v12, v1, s[4:5] sc1
	v_readlane_b32 s4, v250, 1
	v_readlane_b32 s5, v250, 2
	s_nop 4
	global_load_dword v13, v1, s[4:5] sc1
	v_readlane_b32 s4, v250, 3
	v_readlane_b32 s5, v250, 4
	s_nop 4
	global_load_dword v14, v1, s[4:5] sc1
	v_readlane_b32 s4, v250, 5
	v_readlane_b32 s5, v250, 6
	s_nop 4
	global_load_dword v15, v1, s[4:5] sc1
	v_readlane_b32 s4, v250, 7
	v_readlane_b32 s5, v250, 8
	s_nop 4
	global_load_dword v16, v1, s[4:5] sc1
	s_mov_b64 s[4:5], -1
	s_waitcnt vmcnt(0)
	v_add_u32_e32 v17, v2, v0
	v_add_u32_e32 v17, v17, v3
	v_add_u32_e32 v17, v17, v4
	v_add_u32_e32 v17, v17, v5
	v_add_u32_e32 v17, v17, v6
	v_add_u32_e32 v17, v17, v7
	v_add_u32_e32 v17, v17, v8
	v_add_u32_e32 v17, v17, v9
	v_add_u32_e32 v17, v17, v10
	v_add_u32_e32 v17, v17, v11
	v_add_u32_e32 v17, v17, v12
	v_add_u32_e32 v17, v17, v13
	v_add_u32_e32 v17, v17, v14
	v_add_u32_e32 v17, v17, v15
	v_add_u32_e32 v17, v17, v16
	v_cmp_eq_u32_e32 vcc, s19, v17
	s_cbranch_vccnz .LBB0_327
	s_and_b32 s4, s18, 0xff
	s_cmp_eq_u32 s4, 0
	s_mov_b64 s[4:5], -1
	s_mov_b64 s[40:41], -1
	s_sleep 1
	s_cbranch_scc1 .LBB0_332
	s_and_b64 vcc, exec, s[40:41]
	s_cbranch_vccz .LBB0_327
